# F1 K-loop: A-fragment and B-fragment register positions swapped (B fragments now v162..v227, A fragments v66..v161), pure rename inside the loop
# baseline (speedup 1.0000x reference)
; #define PG8_STAGE(bufoff, gbase, voff) do { _Pragma("unroll") for (int _i = 0; _i < 2; ++_i) \
;         __builtin_amdgcn_global_load_lds((const unsigned*)((const char*)(gbase) + (voff)[_i]), (PG8_LAS unsigned*)(lds + (bufoff) + ldsw + _i * 8192), 16, 0, 0); } while (0)
; #define PG8_LDA(dst, b, h) do { _Pragma("unroll") for (int m = 0; m < 4; ++m) _Pragma("unroll") for (int k = 0; k < 2; ++k) dst[m][k] = *(const PG8_LAS bf16x8*)(lds + PG8_SA(b, h) + aoff + m * 2048 + k * 1024); } while (0)
; #define PG8_LDB(dst, b, h) do { _Pragma("unroll") for (int n = 0; n < 2; ++n) _Pragma("unroll") for (int k = 0; k < 2; ++k) dst[n][k] = *(const PG8_LAS bf16x8*)(lds + PG8_SB(b, h) + boff + n * 2048 + k * 1024); } while (0)
; #define PG8_WAIT_L(n) asm volatile("s_waitcnt lgkmcnt(" #n ")" ::: "memory")
; #define PG8_WAIT_V_SEL(sel) asm volatile("s_cmp_eq_u32 %0, 0\n\ts_cbranch_scc1 .Lw8_%=\n\ts_waitcnt vmcnt(22)\n\ts_branch .Lwd_%=\n.Lw8_%=:\n\ts_waitcnt vmcnt(8)\n.Lwd_%=:" :: "s"(sel) : "memory", "scc")
; #define PG8_BAR __builtin_amdgcn_s_barrier()
; #define PG8_SCHED __builtin_amdgcn_sched_barrier(0)
;     ...
;             const bool last = (t == nt * KREP - 2);
;             const int t1w = KREP > 1 ? ((t + 1) & (nt - 1)) : t + 1, t2w = KREP > 1 ? ((t + 2) & (nt - 1)) : t + 2;
;             const char* a1 = cA + (size_t)t1w * kstep;
;             const char* a2 = last ? nA : cA + (size_t)t2w * kstep; const char* b2 = last ? nB : cB + (size_t)t2w * kstep;
;             const char* a3 = a2 + kstep; const char* b3 = b2 + kstep;
;             if (last && has_next) S.a_ready(nxt);
;             const int relax = __builtin_amdgcn_readfirstlane((MK_RELAXW && t == 0 && ui > 0) ? 1 : 0);
;             if constexpr (SP2) {
;             PG8_LDB(B0, 0, 0); PG8_LDB(B1, 0, 1); PG8_SCHED; PG8_LDA(At, 0, 0); PG8_STAGE(PG8_SA(1, 1), a1 + hstep, voffA);
;             PG8_WAIT_V_SEL(relax);
;             PG8_WAIT_L(0); PG8_BAR; PG8_MMA(0, 0, At, B0); PG8_MMA(0, 1, At, B1); PG8_BAR; PG8_SCHED;
;             PG8_LDA(At, 0, 1); PG8_STAGE(PG8_SB(0, 0), b2, voffB); PG8_STAGE(PG8_SB(0, 1), b2 + hstep, voffB); PG8_STAGE(PG8_SA(0, 0), a2, voffA);
;             PG8_WAIT_V_SEL(relax);
;             PG8_WAIT_L(0); PG8_BAR; PG8_MMA(1, 0, At, B0); PG8_MMA(1, 1, At, B1); PG8_BAR; PG8_SCHED;
.LBB0_1327:
	s_add_u32 s96, s12, 0x100
	s_addc_u32 s97, s13, 0
	s_add_i32 s51, 0, 0x10000
	s_cmp_eq_u32 s0, 28
	s_cselect_b32 s41, s59, s97
	s_cselect_b32 s40, s64, s96
	s_cselect_b32 vcc_hi, s65, s67
	s_cselect_b32 vcc_lo, s87, s66
	s_add_i32 s19, 0, 0x14000
	ds_read_b128 v[162:165], v200
	ds_read_b128 v[166:169], v200 offset:1024
	ds_read_b128 v[170:173], v200 offset:2048
	ds_read_b128 v[174:177], v200 offset:3072
	ds_read_b128 v[178:181], v200 offset:16384
	ds_read_b128 v[184:187], v200 offset:17408
	ds_read_b128 v[220:223], v200 offset:18432
	ds_read_b128 v[224:227], v200 offset:19456
	s_add_i32 m0, s95, 0xc000
	ds_read_b128 v[66:69], v219
	ds_read_b128 v[70:73], v219 offset:1024
	ds_read_b128 v[82:85], v219 offset:2048
	ds_read_b128 v[142:145], v219 offset:3072
	ds_read_b128 v[146:149], v219 offset:4096
	ds_read_b128 v[150:153], v219 offset:5120
	ds_read_b128 v[154:157], v219 offset:6144
	ds_read_b128 v[158:161], v219 offset:7168
	global_load_lds_dwordx4 v196, s[12:13]
	s_add_i32 m0, s95, 0xe000
	s_nop 0
	global_load_lds_dwordx4 v198, s[12:13]
	s_cmp_eq_u32 s101, 1
	s_cbranch_scc1 .Lrlx_f1_0
	s_waitcnt vmcnt(8)
.Lrlx_f1_0_b:
	s_waitcnt lgkmcnt(0)
	.p2align 3
	s_setprio 1
	s_barrier
	v_mfma_f32_16x16x32_bf16 v[114:117], v[162:165], v[66:69], v[114:117]
	v_mfma_f32_16x16x32_bf16 v[114:117], v[166:169], v[70:73], v[114:117]
	v_mfma_f32_16x16x32_bf16 v[110:113], v[162:165], v[82:85], v[110:113]
	v_mfma_f32_16x16x32_bf16 v[110:113], v[166:169], v[142:145], v[110:113]
	v_mfma_f32_16x16x32_bf16 v[78:81], v[162:165], v[146:149], v[78:81]
	v_mfma_f32_16x16x32_bf16 v[78:81], v[166:169], v[150:153], v[78:81]
	v_mfma_f32_16x16x32_bf16 v[74:77], v[162:165], v[154:157], v[74:77]
	v_mfma_f32_16x16x32_bf16 v[74:77], v[166:169], v[158:161], v[74:77]
	v_mfma_f32_16x16x32_bf16 v[134:137], v[170:173], v[154:157], v[134:137]
	v_mfma_f32_16x16x32_bf16 v[134:137], v[174:177], v[158:161], v[134:137]
	v_mfma_f32_16x16x32_bf16 v[138:141], v[170:173], v[146:149], v[138:141]
	v_mfma_f32_16x16x32_bf16 v[138:141], v[174:177], v[150:153], v[138:141]
	v_mfma_f32_16x16x32_bf16 v[102:105], v[170:173], v[82:85], v[102:105]
	v_mfma_f32_16x16x32_bf16 v[102:105], v[174:177], v[142:145], v[102:105]
	v_mfma_f32_16x16x32_bf16 v[106:109], v[170:173], v[66:69], v[106:109]
	v_mfma_f32_16x16x32_bf16 v[106:109], v[174:177], v[70:73], v[106:109]
	v_mfma_f32_16x16x32_bf16 v[98:101], v[178:181], v[66:69], v[98:101]
	v_mfma_f32_16x16x32_bf16 v[98:101], v[184:187], v[70:73], v[98:101]
	v_mfma_f32_16x16x32_bf16 v[94:97], v[178:181], v[82:85], v[94:97]
	v_mfma_f32_16x16x32_bf16 v[94:97], v[184:187], v[142:145], v[94:97]
	v_mfma_f32_16x16x32_bf16 v[130:133], v[178:181], v[146:149], v[130:133]
	v_mfma_f32_16x16x32_bf16 v[130:133], v[184:187], v[150:153], v[130:133]
	v_mfma_f32_16x16x32_bf16 v[126:129], v[178:181], v[154:157], v[126:129]
	v_mfma_f32_16x16x32_bf16 v[126:129], v[184:187], v[158:161], v[126:129]
	v_mfma_f32_16x16x32_bf16 v[118:121], v[220:223], v[154:157], v[118:121]
	v_mfma_f32_16x16x32_bf16 v[118:121], v[224:227], v[158:161], v[118:121]
	v_mfma_f32_16x16x32_bf16 v[122:125], v[220:223], v[146:149], v[122:125]
	v_mfma_f32_16x16x32_bf16 v[122:125], v[224:227], v[150:153], v[122:125]
	v_mfma_f32_16x16x32_bf16 v[86:89], v[220:223], v[82:85], v[86:89]
	v_mfma_f32_16x16x32_bf16 v[86:89], v[224:227], v[142:145], v[86:89]
	v_mfma_f32_16x16x32_bf16 v[90:93], v[220:223], v[66:69], v[90:93]
	v_mfma_f32_16x16x32_bf16 v[90:93], v[224:227], v[70:73], v[90:93]
	s_barrier
	s_setprio 0
	s_add_i32 s12, s51, s37
	s_mov_b32 m0, s12
	ds_read_b128 v[66:69], v219 offset:16384
	ds_read_b128 v[70:73], v219 offset:17408
	ds_read_b128 v[82:85], v219 offset:18432
	ds_read_b128 v[142:145], v219 offset:19456
	ds_read_b128 v[146:149], v219 offset:20480
	ds_read_b128 v[150:153], v219 offset:21504
	ds_read_b128 v[154:157], v219 offset:22528
	ds_read_b128 v[158:161], v219 offset:23552
	global_load_lds_dwordx4 v182, vcc
	s_add_i32 m0, s12, 0x2000
	s_add_u32 s12, vcc_lo, 0x80000
	s_addc_u32 s13, vcc_hi, 0
	s_add_i32 s19, s19, s37
	global_load_lds_dwordx4 v192, vcc
	s_mov_b32 m0, s19
	s_nop 0
	global_load_lds_dwordx4 v182, s[12:13]
	s_add_i32 m0, s19, 0x2000
	s_nop 0
	global_load_lds_dwordx4 v192, s[12:13]
	s_mov_b32 m0, s95
	s_nop 0
	global_load_lds_dwordx4 v188, s[40:41]
	s_mov_b32 m0, s20
	s_nop 0
	global_load_lds_dwordx4 v190, s[40:41]
	s_cmp_eq_u32 s101, 1
	s_cbranch_scc1 .Lrlx_f1_1
	s_waitcnt vmcnt(8)
; #define PG8_STAGE(bufoff, gbase, voff) do { _Pragma("unroll") for (int _i = 0; _i < 2; ++_i) \
;         __builtin_amdgcn_global_load_lds((const unsigned*)((const char*)(gbase) + (voff)[_i]), (PG8_LAS unsigned*)(lds + (bufoff) + ldsw + _i * 8192), 16, 0, 0); } while (0)
; #define PG8_LDA(dst, b, h) do { _Pragma("unroll") for (int m = 0; m < 4; ++m) _Pragma("unroll") for (int k = 0; k < 2; ++k) dst[m][k] = *(const PG8_LAS bf16x8*)(lds + PG8_SA(b, h) + aoff + m * 2048 + k * 1024); } while (0)
; #define PG8_LDB(dst, b, h) do { _Pragma("unroll") for (int n = 0; n < 2; ++n) _Pragma("unroll") for (int k = 0; k < 2; ++k) dst[n][k] = *(const PG8_LAS bf16x8*)(lds + PG8_SB(b, h) + boff + n * 2048 + k * 1024); } while (0)
; #define PG8_WAIT_V(n) asm volatile("s_waitcnt vmcnt(" #n ")" ::: "memory")
; #define PG8_WAIT_L(n) asm volatile("s_waitcnt lgkmcnt(" #n ")" ::: "memory")
; #define PG8_BAR __builtin_amdgcn_s_barrier()
; #define PG8_SCHED __builtin_amdgcn_sched_barrier(0)
;     ...
;             PG8_WAIT_L(0); PG8_BAR; PG8_MMA(1, 0, At, B0); PG8_MMA(1, 1, At, B1); PG8_BAR; PG8_SCHED;
;             PG8_LDB(B0, 1, 0); PG8_LDB(B1, 1, 1); PG8_SCHED; PG8_LDA(At, 1, 0); PG8_STAGE(PG8_SA(0, 1), a2 + hstep, voffA);
;             PG8_WAIT_V(8); PG8_WAIT_L(0); PG8_BAR; PG8_MMA(0, 0, At, B0); PG8_MMA(0, 1, At, B1); PG8_BAR; PG8_SCHED;
.Lrlx_f1_1_b:
	s_waitcnt lgkmcnt(0)
	.p2align 3
	s_setprio 1
	s_barrier
	v_mfma_f32_16x16x32_bf16 v[30:33], v[162:165], v[66:69], v[30:33]
	v_mfma_f32_16x16x32_bf16 v[30:33], v[166:169], v[70:73], v[30:33]
	v_mfma_f32_16x16x32_bf16 v[26:29], v[162:165], v[82:85], v[26:29]
	v_mfma_f32_16x16x32_bf16 v[26:29], v[166:169], v[142:145], v[26:29]
	v_mfma_f32_16x16x32_bf16 v[62:65], v[162:165], v[146:149], v[62:65]
	v_mfma_f32_16x16x32_bf16 v[62:65], v[166:169], v[150:153], v[62:65]
	v_mfma_f32_16x16x32_bf16 v[58:61], v[162:165], v[154:157], v[58:61]
	v_mfma_f32_16x16x32_bf16 v[58:61], v[166:169], v[158:161], v[58:61]
	v_mfma_f32_16x16x32_bf16 v[50:53], v[170:173], v[154:157], v[50:53]
	v_mfma_f32_16x16x32_bf16 v[50:53], v[174:177], v[158:161], v[50:53]
	v_mfma_f32_16x16x32_bf16 v[54:57], v[170:173], v[146:149], v[54:57]
	v_mfma_f32_16x16x32_bf16 v[54:57], v[174:177], v[150:153], v[54:57]
	v_mfma_f32_16x16x32_bf16 v[18:21], v[170:173], v[82:85], v[18:21]
	v_mfma_f32_16x16x32_bf16 v[18:21], v[174:177], v[142:145], v[18:21]
	v_mfma_f32_16x16x32_bf16 v[22:25], v[170:173], v[66:69], v[22:25]
	v_mfma_f32_16x16x32_bf16 v[22:25], v[174:177], v[70:73], v[22:25]
	v_mfma_f32_16x16x32_bf16 v[14:17], v[178:181], v[66:69], v[14:17]
	v_mfma_f32_16x16x32_bf16 v[14:17], v[184:187], v[70:73], v[14:17]
	v_mfma_f32_16x16x32_bf16 v[10:13], v[178:181], v[82:85], v[10:13]
	v_mfma_f32_16x16x32_bf16 v[10:13], v[184:187], v[142:145], v[10:13]
	v_mfma_f32_16x16x32_bf16 v[46:49], v[178:181], v[146:149], v[46:49]
	v_mfma_f32_16x16x32_bf16 v[46:49], v[184:187], v[150:153], v[46:49]
	v_mfma_f32_16x16x32_bf16 v[38:41], v[178:181], v[154:157], v[38:41]
	v_mfma_f32_16x16x32_bf16 v[38:41], v[184:187], v[158:161], v[38:41]
	v_mfma_f32_16x16x32_bf16 v[42:45], v[220:223], v[154:157], v[42:45]
	v_mfma_f32_16x16x32_bf16 v[42:45], v[224:227], v[158:161], v[42:45]
	v_mfma_f32_16x16x32_bf16 v[34:37], v[220:223], v[146:149], v[34:37]
	v_mfma_f32_16x16x32_bf16 v[34:37], v[224:227], v[150:153], v[34:37]
	v_mfma_f32_16x16x32_bf16 v[2:5], v[220:223], v[82:85], v[2:5]
	v_mfma_f32_16x16x32_bf16 v[2:5], v[224:227], v[142:145], v[2:5]
	v_mfma_f32_16x16x32_bf16 v[6:9], v[220:223], v[66:69], v[6:9]
	v_mfma_f32_16x16x32_bf16 v[6:9], v[224:227], v[70:73], v[6:9]
	s_barrier
	s_setprio 0
	s_add_i32 s19, 0, 0x18000
	s_add_i32 s51, 0, 0x1c000
	ds_read_b128 v[162:165], v200 offset:32768
	ds_read_b128 v[166:169], v200 offset:33792
	ds_read_b128 v[170:173], v200 offset:34816
	ds_read_b128 v[174:177], v200 offset:35840
	ds_read_b128 v[178:181], v200 offset:49152
	ds_read_b128 v[184:187], v200 offset:50176
	ds_read_b128 v[220:223], v200 offset:51200
	ds_read_b128 v[224:227], v200 offset:52224
	s_add_u32 s12, s40, 0x80000
	s_addc_u32 s13, s41, 0
	s_mov_b32 m0, s44
	ds_read_b128 v[66:69], v219 offset:32768
	ds_read_b128 v[70:73], v219 offset:33792
	ds_read_b128 v[82:85], v219 offset:34816
	ds_read_b128 v[142:145], v219 offset:35840
	ds_read_b128 v[146:149], v219 offset:36864
	ds_read_b128 v[150:153], v219 offset:37888
	ds_read_b128 v[154:157], v219 offset:38912
	ds_read_b128 v[158:161], v219 offset:39936
	global_load_lds_dwordx4 v188, s[12:13]
	s_mov_b32 m0, s46
	s_nop 0
	global_load_lds_dwordx4 v190, s[12:13]
	s_waitcnt vmcnt(8)
	s_waitcnt lgkmcnt(0)
	.p2align 3
	s_setprio 1
	s_barrier
	v_mfma_f32_16x16x32_bf16 v[114:117], v[162:165], v[66:69], v[114:117]
	v_mfma_f32_16x16x32_bf16 v[114:117], v[166:169], v[70:73], v[114:117]
	v_mfma_f32_16x16x32_bf16 v[110:113], v[162:165], v[82:85], v[110:113]
	v_mfma_f32_16x16x32_bf16 v[110:113], v[166:169], v[142:145], v[110:113]
	v_mfma_f32_16x16x32_bf16 v[78:81], v[162:165], v[146:149], v[78:81]
	v_mfma_f32_16x16x32_bf16 v[78:81], v[166:169], v[150:153], v[78:81]
	v_mfma_f32_16x16x32_bf16 v[74:77], v[162:165], v[154:157], v[74:77]
	v_mfma_f32_16x16x32_bf16 v[74:77], v[166:169], v[158:161], v[74:77]
	v_mfma_f32_16x16x32_bf16 v[134:137], v[170:173], v[154:157], v[134:137]
	v_mfma_f32_16x16x32_bf16 v[134:137], v[174:177], v[158:161], v[134:137]
	v_mfma_f32_16x16x32_bf16 v[138:141], v[170:173], v[146:149], v[138:141]
	v_mfma_f32_16x16x32_bf16 v[138:141], v[174:177], v[150:153], v[138:141]
	v_mfma_f32_16x16x32_bf16 v[102:105], v[170:173], v[82:85], v[102:105]
	v_mfma_f32_16x16x32_bf16 v[102:105], v[174:177], v[142:145], v[102:105]
	v_mfma_f32_16x16x32_bf16 v[106:109], v[170:173], v[66:69], v[106:109]
	v_mfma_f32_16x16x32_bf16 v[106:109], v[174:177], v[70:73], v[106:109]
	v_mfma_f32_16x16x32_bf16 v[98:101], v[178:181], v[66:69], v[98:101]
	v_mfma_f32_16x16x32_bf16 v[98:101], v[184:187], v[70:73], v[98:101]
	v_mfma_f32_16x16x32_bf16 v[94:97], v[178:181], v[82:85], v[94:97]
	v_mfma_f32_16x16x32_bf16 v[94:97], v[184:187], v[142:145], v[94:97]
	v_mfma_f32_16x16x32_bf16 v[130:133], v[178:181], v[146:149], v[130:133]
	v_mfma_f32_16x16x32_bf16 v[130:133], v[184:187], v[150:153], v[130:133]
	v_mfma_f32_16x16x32_bf16 v[126:129], v[178:181], v[154:157], v[126:129]
	v_mfma_f32_16x16x32_bf16 v[126:129], v[184:187], v[158:161], v[126:129]
	v_mfma_f32_16x16x32_bf16 v[118:121], v[220:223], v[154:157], v[118:121]
	v_mfma_f32_16x16x32_bf16 v[118:121], v[224:227], v[158:161], v[118:121]
	v_mfma_f32_16x16x32_bf16 v[122:125], v[220:223], v[146:149], v[122:125]
	v_mfma_f32_16x16x32_bf16 v[122:125], v[224:227], v[150:153], v[122:125]
	v_mfma_f32_16x16x32_bf16 v[86:89], v[220:223], v[82:85], v[86:89]
	v_mfma_f32_16x16x32_bf16 v[86:89], v[224:227], v[142:145], v[86:89]
	v_mfma_f32_16x16x32_bf16 v[90:93], v[220:223], v[66:69], v[90:93]
	v_mfma_f32_16x16x32_bf16 v[90:93], v[224:227], v[70:73], v[90:93]
	s_barrier
; #define PG8_STAGE(bufoff, gbase, voff) do { _Pragma("unroll") for (int _i = 0; _i < 2; ++_i) \
;         __builtin_amdgcn_global_load_lds((const unsigned*)((const char*)(gbase) + (voff)[_i]), (PG8_LAS unsigned*)(lds + (bufoff) + ldsw + _i * 8192), 16, 0, 0); } while (0)
; #define PG8_LDA(dst, b, h) do { _Pragma("unroll") for (int m = 0; m < 4; ++m) _Pragma("unroll") for (int k = 0; k < 2; ++k) dst[m][k] = *(const PG8_LAS bf16x8*)(lds + PG8_SA(b, h) + aoff + m * 2048 + k * 1024); } while (0)
; #define PG8_WAIT_V(n) asm volatile("s_waitcnt vmcnt(" #n ")" ::: "memory")
; #define PG8_WAIT_L(n) asm volatile("s_waitcnt lgkmcnt(" #n ")" ::: "memory")
; #define PG8_BAR __builtin_amdgcn_s_barrier()
; #define PG8_SCHED __builtin_amdgcn_sched_barrier(0)
;     ...
;         for (int t = 0; t < nt * KREP; t += 2) {
;             const bool last = (t == nt * KREP - 2);
;     ...
;             PG8_LDA(At, 1, 1); PG8_STAGE(PG8_SB(1, 0), b3, voffB); PG8_STAGE(PG8_SB(1, 1), b3 + hstep, voffB); PG8_STAGE(PG8_SA(1, 0), a3, voffA);
;             PG8_WAIT_V(8); PG8_WAIT_L(0); PG8_BAR; PG8_MMA(1, 0, At, B0); PG8_MMA(1, 1, At, B1); PG8_BAR; PG8_SCHED;
	s_setprio 0
	s_add_i32 s12, s19, s37
	s_mov_b32 m0, s12
	ds_read_b128 v[66:69], v219 offset:49152
	ds_read_b128 v[70:73], v219 offset:50176
	ds_read_b128 v[82:85], v219 offset:51200
	ds_read_b128 v[142:145], v219 offset:52224
	ds_read_b128 v[146:149], v219 offset:53248
	ds_read_b128 v[150:153], v219 offset:54272
	ds_read_b128 v[154:157], v219 offset:55296
	ds_read_b128 v[158:161], v219 offset:56320
	s_add_u32 s100, vcc_lo, 0x80
	s_addc_u32 s101, vcc_hi, 0
	global_load_lds_dwordx4 v182, s[100:101]
	s_add_i32 m0, s12, 0x2000
	s_add_u32 s12, vcc_lo, 0x80080
	s_addc_u32 s13, vcc_hi, 0
	s_add_i32 s19, s51, s37
	global_load_lds_dwordx4 v192, s[100:101]
	s_mov_b32 m0, s19
	s_nop 0
	global_load_lds_dwordx4 v182, s[12:13]
	s_add_i32 m0, s19, 0x2000
	s_nop 0
	global_load_lds_dwordx4 v192, s[12:13]
	s_mov_b32 m0, s45
	s_nop 0
	s_add_u32 s100, s40, 0x80
	s_addc_u32 s101, s41, 0
	global_load_lds_dwordx4 v188, s[100:101]
	s_mov_b32 m0, s24
	s_nop 0
	global_load_lds_dwordx4 v190, s[100:101]
	s_waitcnt vmcnt(8)
	s_waitcnt lgkmcnt(0)
	.p2align 3
	s_setprio 1
	s_barrier
	v_mfma_f32_16x16x32_bf16 v[30:33], v[162:165], v[66:69], v[30:33]
	v_mfma_f32_16x16x32_bf16 v[30:33], v[166:169], v[70:73], v[30:33]
	v_mfma_f32_16x16x32_bf16 v[26:29], v[162:165], v[82:85], v[26:29]
	v_mfma_f32_16x16x32_bf16 v[26:29], v[166:169], v[142:145], v[26:29]
	v_mfma_f32_16x16x32_bf16 v[62:65], v[162:165], v[146:149], v[62:65]
	v_mfma_f32_16x16x32_bf16 v[62:65], v[166:169], v[150:153], v[62:65]
	v_mfma_f32_16x16x32_bf16 v[58:61], v[162:165], v[154:157], v[58:61]
	v_mfma_f32_16x16x32_bf16 v[58:61], v[166:169], v[158:161], v[58:61]
	v_mfma_f32_16x16x32_bf16 v[50:53], v[170:173], v[154:157], v[50:53]
	v_mfma_f32_16x16x32_bf16 v[50:53], v[174:177], v[158:161], v[50:53]
	v_mfma_f32_16x16x32_bf16 v[54:57], v[170:173], v[146:149], v[54:57]
	v_mfma_f32_16x16x32_bf16 v[54:57], v[174:177], v[150:153], v[54:57]
	v_mfma_f32_16x16x32_bf16 v[18:21], v[170:173], v[82:85], v[18:21]
	v_mfma_f32_16x16x32_bf16 v[18:21], v[174:177], v[142:145], v[18:21]
	v_mfma_f32_16x16x32_bf16 v[22:25], v[170:173], v[66:69], v[22:25]
	v_mfma_f32_16x16x32_bf16 v[22:25], v[174:177], v[70:73], v[22:25]
	v_mfma_f32_16x16x32_bf16 v[14:17], v[178:181], v[66:69], v[14:17]
	v_mfma_f32_16x16x32_bf16 v[14:17], v[184:187], v[70:73], v[14:17]
	v_mfma_f32_16x16x32_bf16 v[10:13], v[178:181], v[82:85], v[10:13]
	v_mfma_f32_16x16x32_bf16 v[10:13], v[184:187], v[142:145], v[10:13]
	v_mfma_f32_16x16x32_bf16 v[46:49], v[178:181], v[146:149], v[46:49]
	v_mfma_f32_16x16x32_bf16 v[46:49], v[184:187], v[150:153], v[46:49]
	v_mfma_f32_16x16x32_bf16 v[38:41], v[178:181], v[154:157], v[38:41]
	v_mfma_f32_16x16x32_bf16 v[38:41], v[184:187], v[158:161], v[38:41]
	v_mfma_f32_16x16x32_bf16 v[42:45], v[220:223], v[154:157], v[42:45]
	v_mfma_f32_16x16x32_bf16 v[42:45], v[224:227], v[158:161], v[42:45]
	v_mfma_f32_16x16x32_bf16 v[34:37], v[220:223], v[146:149], v[34:37]
	v_mfma_f32_16x16x32_bf16 v[34:37], v[224:227], v[150:153], v[34:37]
	v_mfma_f32_16x16x32_bf16 v[2:5], v[220:223], v[82:85], v[2:5]
	v_mfma_f32_16x16x32_bf16 v[2:5], v[224:227], v[142:145], v[2:5]
	v_mfma_f32_16x16x32_bf16 v[6:9], v[220:223], v[66:69], v[6:9]
	v_mfma_f32_16x16x32_bf16 v[6:9], v[224:227], v[70:73], v[6:9]
	s_barrier
	s_setprio 0
	s_add_i32 s0, s0, 2
	s_add_u32 s66, s66, 0x100
	s_addc_u32 s67, s67, 0
	s_cmp_gt_u32 s0, 29
	s_mov_b64 s[12:13], s[96:97]
	s_mov_b32 s101, 0
	s_cbranch_scc0 .LBB0_1327
	s_branch .Lrlx_f1_x
